# GEMM: first K-loop trip peeled, first-touch MFMAs use SrcC=0 (no accumulator zeroing at tile head), static first-trip wait skip
# baseline (speedup 1.0000x reference)
; #define PG8_STAGE(bufoff, gbase, voff) do { _Pragma("unroll") for (int _i = 0; _i < 2; ++_i) \
;     __builtin_amdgcn_global_load_lds((const unsigned*)((const char*)(gbase) + (voff)[_i]), (LAS unsigned*)(lds + (bufoff) + ldsw + _i * 8192), 16, 0, 0); } while (0)
; #define PG8_LDA(dst, b, h) do { _Pragma("unroll") for (int m = 0; m < 4; ++m) _Pragma("unroll") for (int k = 0; k < 2; ++k) dst[m][k] = *(const LAS bf16x8*)(lds + PG8_SA(b, h) + aoff + m * 2048 + k * 1024); } while (0)
; #define PG8_LDB(dst, b, h) do { _Pragma("unroll") for (int n = 0; n < 2; ++n) _Pragma("unroll") for (int k = 0; k < 2; ++k) dst[n][k] = *(const LAS bf16x8*)(lds + PG8_SB(b, h) + boff + n * 2048 + k * 1024); } while (0)
; #define PG8_MMA(ai, bj, At, Bt) do { __builtin_amdgcn_s_setprio(1); _Pragma("unroll") for (int m = 0; m < 4; ++m) _Pragma("unroll") for (int n = 0; n < 2; ++n) _Pragma("unroll") for (int k = 0; k < 2; ++k) \
;     acc[ai][bj][m][n] = __builtin_amdgcn_mfma_f32_16x16x32_bf16(Bt[n][k], At[m][k], acc[ai][bj][m][n], 0, 0, 0); __builtin_amdgcn_s_setprio(0); } while (0)
; #define PG8_WAIT_V(n) asm volatile("s_waitcnt vmcnt(" #n ")" ::: "memory")
; #define PG8_WAIT_L(n) asm volatile("s_waitcnt lgkmcnt(" #n ")" ::: "memory")
; #define PG8_BAR __builtin_amdgcn_s_barrier()
; #define PG8_SCHED __builtin_amdgcn_sched_barrier(0)
; template <class Epi>
; __device__ __forceinline__ void gemm_phase(LAS unsigned char* lds, const Gemm g, const StaticOrder& S, const Epi& E) {
;     ...
;     for (int t = 0; t < nt; t += 2) {
;       const bool last = (t == nt - 2);
;       const char* a1 = cA + (size_t)(t + 1) * kstep;
;       const char* a2 = last ? nA : cA + (size_t)(t + 2) * kstep; const char* b2 = last ? nB : cB + (size_t)(t + 2) * kstep;
;       const char* a3 = a2 + kstep; const char* b3 = b2 + kstep;
;       PG8_LDB(B0, 0, 0); PG8_SCHED; PG8_LDA(At, 0, 0); PG8_STAGE(PG8_SA(1, 1), a1 + hstep, voffA);
;       PG8_WAIT_L(8); PG8_BAR; PG8_WAIT_L(0); PG8_MMA(0, 0, At, B0); PG8_BAR; PG8_SCHED;
;       PG8_LDB(B1, 0, 1); PG8_STAGE(PG8_SB(0, 0), b2, voffB);
;       PG8_BAR; PG8_WAIT_L(0); PG8_MMA(0, 1, At, B1); PG8_BAR;
;       PG8_LDA(At, 0, 1); PG8_STAGE(PG8_SA(0, 0), a2, voffA);
;       PG8_BAR; PG8_WAIT_L(0); PG8_MMA(1, 0, At, B0); PG8_BAR; PG8_SCHED;
;       PG8_STAGE(PG8_SB(0, 1), b2 + hstep, voffB);
;       PG8_WAIT_V(6); PG8_BAR; PG8_MMA(1, 1, At, B1); PG8_BAR;
.LBB0_55:
	s_add_u32 s74, s12, 0x100
	s_addc_u32 s75, s13, 0
	s_add_u32 s0, s10, 0x80
	s_addc_u32 s1, s11, 0
	s_mov_b32 s10, 0
	s_add_i32 s76, s10, 2
	s_add_u32 s12, s0, 0x80
	s_addc_u32 s11, s1, 0
	s_add_i32 s77, 0, 0x10000
	v_add_u32_e32 v80, s77, v187
	ds_read_b128 v[130:133], v80
	ds_read_b128 v[134:137], v80 offset:1024
	ds_read_b128 v[138:141], v80 offset:2048
	ds_read_b128 v[142:145], v80 offset:3072
	s_cmp_eq_u32 s21, s10
	s_cselect_b32 s10, s18, s12
	s_cselect_b32 s11, s19, s11
	s_cselect_b32 s13, s17, s75
	s_cselect_b32 s12, s16, s74
	v_lshl_add_u64 v[244:245], s[0:1], 0, v[172:173]
	s_add_i32 m0, s15, 0xc000
	ds_read_b128 v[146:149], v189
	ds_read_b128 v[150:153], v189 offset:1024
	ds_read_b128 v[154:157], v189 offset:2048
	ds_read_b128 v[158:161], v189 offset:3072
	ds_read_b128 v[174:177], v189 offset:4096
	ds_read_b128 v[178:181], v189 offset:5120
	ds_read_b128 v[182:185], v189 offset:6144
	ds_read_b128 v[190:193], v189 offset:7168
	global_load_lds_dwordx4 v[244:245], off
	v_lshl_add_u64 v[246:247], s[0:1], 0, v[170:171]
	s_add_i32 m0, s15, 0xe000
	ds_read_b128 v[194:197], v80 offset:16384
	ds_read_b128 v[198:201], v80 offset:17408
	ds_read_b128 v[202:205], v80 offset:18432
	ds_read_b128 v[206:209], v80 offset:19456
	global_load_lds_dwordx4 v[246:247], off
	s_waitcnt lgkmcnt(0)
	s_barrier
	v_mfma_f32_16x16x32_bf16 v[126:129], v[130:133], v[146:149], 0
	v_mfma_f32_16x16x32_bf16 v[122:125], v[138:141], v[146:149], 0
	v_mfma_f32_16x16x32_bf16 v[118:121], v[130:133], v[154:157], 0
	v_mfma_f32_16x16x32_bf16 v[114:117], v[138:141], v[154:157], 0
	v_mfma_f32_16x16x32_bf16 v[110:113], v[130:133], v[174:177], 0
	v_mfma_f32_16x16x32_bf16 v[106:109], v[138:141], v[174:177], 0
	v_mfma_f32_16x16x32_bf16 v[102:105], v[130:133], v[182:185], 0
	v_mfma_f32_16x16x32_bf16 v[98:101], v[138:141], v[182:185], 0
	v_mfma_f32_16x16x32_bf16 v[126:129], v[134:137], v[150:153], v[126:129]
	v_mfma_f32_16x16x32_bf16 v[122:125], v[142:145], v[150:153], v[122:125]
	v_mfma_f32_16x16x32_bf16 v[118:121], v[134:137], v[158:161], v[118:121]
	v_mfma_f32_16x16x32_bf16 v[114:117], v[142:145], v[158:161], v[114:117]
	v_mfma_f32_16x16x32_bf16 v[110:113], v[134:137], v[178:181], v[110:113]
	v_mfma_f32_16x16x32_bf16 v[106:109], v[142:145], v[178:181], v[106:109]
	v_mfma_f32_16x16x32_bf16 v[102:105], v[134:137], v[190:193], v[102:105]
	v_mfma_f32_16x16x32_bf16 v[98:101], v[142:145], v[190:193], v[98:101]
	v_mfma_f32_16x16x32_bf16 v[60:63], v[194:197], v[146:149], 0
	v_mfma_f32_16x16x32_bf16 v[56:59], v[202:205], v[146:149], 0
	v_mfma_f32_16x16x32_bf16 v[52:55], v[194:197], v[154:157], 0
	v_mfma_f32_16x16x32_bf16 v[48:51], v[202:205], v[154:157], 0
	v_mfma_f32_16x16x32_bf16 v[44:47], v[194:197], v[174:177], 0
	v_mfma_f32_16x16x32_bf16 v[40:43], v[202:205], v[174:177], 0
	v_mfma_f32_16x16x32_bf16 v[36:39], v[194:197], v[182:185], 0
	v_mfma_f32_16x16x32_bf16 v[32:35], v[202:205], v[182:185], 0
	v_mfma_f32_16x16x32_bf16 v[60:63], v[198:201], v[150:153], v[60:63]
	v_mfma_f32_16x16x32_bf16 v[56:59], v[206:209], v[150:153], v[56:59]
	v_mfma_f32_16x16x32_bf16 v[52:55], v[198:201], v[158:161], v[52:55]
	v_mfma_f32_16x16x32_bf16 v[48:51], v[206:209], v[158:161], v[48:51]
	v_mfma_f32_16x16x32_bf16 v[44:47], v[198:201], v[178:181], v[44:47]
	v_mfma_f32_16x16x32_bf16 v[40:43], v[206:209], v[178:181], v[40:43]
	v_mfma_f32_16x16x32_bf16 v[36:39], v[198:201], v[190:193], v[36:39]
	v_mfma_f32_16x16x32_bf16 v[32:35], v[206:209], v[190:193], v[32:35]
	s_add_i32 s78, 0, 0x14000
	s_add_i32 s77, s77, s14
	s_barrier
	ds_read_b128 v[146:149], v189 offset:16384
	ds_read_b128 v[150:153], v189 offset:17408
	ds_read_b128 v[154:157], v189 offset:18432
	ds_read_b128 v[158:161], v189 offset:19456
	ds_read_b128 v[174:177], v189 offset:20480
	ds_read_b128 v[178:181], v189 offset:21504
	ds_read_b128 v[182:185], v189 offset:22528
	ds_read_b128 v[190:193], v189 offset:23552
	v_lshl_add_u64 v[210:211], s[12:13], 0, v[164:165]
	s_mov_b32 m0, s77
	v_lshl_add_u64 v[212:213], s[12:13], 0, v[168:169]
	global_load_lds_dwordx4 v[210:211], off
	s_add_i32 m0, s77, 0x2000
	v_lshl_add_u64 v[216:217], s[10:11], 0, v[162:163]
	global_load_lds_dwordx4 v[212:213], off
	s_mov_b32 m0, s15
	v_lshl_add_u64 v[232:233], s[10:11], 0, v[166:167]
	global_load_lds_dwordx4 v[216:217], off
	s_mov_b32 m0, s84
	s_add_u32 s12, s12, s64
	s_addc_u32 s13, s13, 0
	global_load_lds_dwordx4 v[232:233], off
	s_add_i32 s77, s78, s14
	v_lshl_add_u64 v[236:237], s[12:13], 0, v[164:165]
	s_mov_b32 m0, s77
	v_lshl_add_u64 v[242:243], s[12:13], 0, v[168:169]
	global_load_lds_dwordx4 v[236:237], off
	s_add_i32 m0, s77, 0x2000
	global_load_lds_dwordx4 v[242:243], off
	s_waitcnt lgkmcnt(0)
	s_barrier
; #define PG8_STAGE(bufoff, gbase, voff) do { _Pragma("unroll") for (int _i = 0; _i < 2; ++_i) \
;     __builtin_amdgcn_global_load_lds((const unsigned*)((const char*)(gbase) + (voff)[_i]), (LAS unsigned*)(lds + (bufoff) + ldsw + _i * 8192), 16, 0, 0); } while (0)
; #define PG8_LDA(dst, b, h) do { _Pragma("unroll") for (int m = 0; m < 4; ++m) _Pragma("unroll") for (int k = 0; k < 2; ++k) dst[m][k] = *(const LAS bf16x8*)(lds + PG8_SA(b, h) + aoff + m * 2048 + k * 1024); } while (0)
; #define PG8_LDB(dst, b, h) do { _Pragma("unroll") for (int n = 0; n < 2; ++n) _Pragma("unroll") for (int k = 0; k < 2; ++k) dst[n][k] = *(const LAS bf16x8*)(lds + PG8_SB(b, h) + boff + n * 2048 + k * 1024); } while (0)
; #define PG8_MMA(ai, bj, At, Bt) do { __builtin_amdgcn_s_setprio(1); _Pragma("unroll") for (int m = 0; m < 4; ++m) _Pragma("unroll") for (int n = 0; n < 2; ++n) _Pragma("unroll") for (int k = 0; k < 2; ++k) \
;     acc[ai][bj][m][n] = __builtin_amdgcn_mfma_f32_16x16x32_bf16(Bt[n][k], At[m][k], acc[ai][bj][m][n], 0, 0, 0); __builtin_amdgcn_s_setprio(0); } while (0)
; #define PG8_WAIT_V(n) asm volatile("s_waitcnt vmcnt(" #n ")" ::: "memory")
; #define PG8_WAIT_L(n) asm volatile("s_waitcnt lgkmcnt(" #n ")" ::: "memory")
; #define PG8_BAR __builtin_amdgcn_s_barrier()
; #define PG8_SCHED __builtin_amdgcn_sched_barrier(0)
; template <class Epi>
; __device__ __forceinline__ void gemm_phase(LAS unsigned char* lds, const Gemm g, const StaticOrder& S, const Epi& E) {
;     ...
;       PG8_BAR; PG8_WAIT_L(0); PG8_MMA(1, 0, At, B0); PG8_BAR; PG8_SCHED;
;       PG8_STAGE(PG8_SB(0, 1), b2 + hstep, voffB);
;       PG8_WAIT_V(6); PG8_BAR; PG8_MMA(1, 1, At, B1); PG8_BAR;
;       PG8_LDB(B0, 1, 0); PG8_SCHED; PG8_LDA(At, 1, 0); PG8_STAGE(PG8_SA(0, 1), a2 + hstep, voffA);
;       PG8_WAIT_L(8); PG8_BAR; PG8_WAIT_L(0); PG8_MMA(0, 0, At, B0); PG8_BAR; PG8_SCHED;
;       PG8_LDB(B1, 1, 1); PG8_STAGE(PG8_SB(1, 0), b3, voffB);
;       PG8_BAR; PG8_WAIT_L(0); PG8_MMA(0, 1, At, B1); PG8_BAR;
	v_mfma_f32_16x16x32_bf16 v[94:97], v[130:133], v[146:149], 0
	v_mfma_f32_16x16x32_bf16 v[90:93], v[138:141], v[146:149], 0
	v_mfma_f32_16x16x32_bf16 v[86:89], v[130:133], v[154:157], 0
	v_mfma_f32_16x16x32_bf16 v[82:85], v[138:141], v[154:157], 0
	v_mfma_f32_16x16x32_bf16 v[76:79], v[130:133], v[174:177], 0
	v_mfma_f32_16x16x32_bf16 v[72:75], v[138:141], v[174:177], 0
	v_mfma_f32_16x16x32_bf16 v[68:71], v[130:133], v[182:185], 0
	v_mfma_f32_16x16x32_bf16 v[64:67], v[138:141], v[182:185], 0
	v_mfma_f32_16x16x32_bf16 v[94:97], v[134:137], v[150:153], v[94:97]
	v_mfma_f32_16x16x32_bf16 v[90:93], v[142:145], v[150:153], v[90:93]
	v_mfma_f32_16x16x32_bf16 v[86:89], v[134:137], v[158:161], v[86:89]
	v_mfma_f32_16x16x32_bf16 v[82:85], v[142:145], v[158:161], v[82:85]
	v_mfma_f32_16x16x32_bf16 v[76:79], v[134:137], v[178:181], v[76:79]
	v_mfma_f32_16x16x32_bf16 v[72:75], v[142:145], v[178:181], v[72:75]
	v_mfma_f32_16x16x32_bf16 v[68:71], v[134:137], v[190:193], v[68:71]
	v_mfma_f32_16x16x32_bf16 v[64:67], v[142:145], v[190:193], v[64:67]
	v_mfma_f32_16x16x32_bf16 v[28:31], v[194:197], v[146:149], 0
	v_mfma_f32_16x16x32_bf16 v[24:27], v[202:205], v[146:149], 0
	v_mfma_f32_16x16x32_bf16 v[20:23], v[194:197], v[154:157], 0
	v_mfma_f32_16x16x32_bf16 v[16:19], v[202:205], v[154:157], 0
	v_mfma_f32_16x16x32_bf16 v[12:15], v[194:197], v[174:177], 0
	v_mfma_f32_16x16x32_bf16 v[8:11], v[202:205], v[174:177], 0
	v_mfma_f32_16x16x32_bf16 v[4:7], v[194:197], v[182:185], 0
	v_mfma_f32_16x16x32_bf16 v[0:3], v[202:205], v[182:185], 0
	v_mfma_f32_16x16x32_bf16 v[28:31], v[198:201], v[150:153], v[28:31]
	v_mfma_f32_16x16x32_bf16 v[24:27], v[206:209], v[150:153], v[24:27]
	v_mfma_f32_16x16x32_bf16 v[20:23], v[198:201], v[158:161], v[20:23]
	v_mfma_f32_16x16x32_bf16 v[16:19], v[206:209], v[158:161], v[16:19]
	v_mfma_f32_16x16x32_bf16 v[12:15], v[198:201], v[178:181], v[12:15]
	v_mfma_f32_16x16x32_bf16 v[8:11], v[206:209], v[178:181], v[8:11]
	v_mfma_f32_16x16x32_bf16 v[4:7], v[198:201], v[190:193], v[4:7]
	v_mfma_f32_16x16x32_bf16 v[0:3], v[206:209], v[190:193], v[0:3]
	s_add_i32 s12, 0, 0x18000
	v_add_u32_e32 v80, s12, v187
	s_barrier
	ds_read_b128 v[130:133], v80
	ds_read_b128 v[134:137], v80 offset:1024
	ds_read_b128 v[138:141], v80 offset:2048
	ds_read_b128 v[142:145], v80 offset:3072
	s_add_u32 s10, s10, s64
	s_addc_u32 s11, s11, 0
	s_mov_b32 m0, s99
	v_lshl_add_u64 v[244:245], s[10:11], 0, v[162:163]
	ds_read_b128 v[146:149], v189 offset:32768
	ds_read_b128 v[150:153], v189 offset:33792
	ds_read_b128 v[154:157], v189 offset:34816
	ds_read_b128 v[158:161], v189 offset:35840
	ds_read_b128 v[174:177], v189 offset:36864
	ds_read_b128 v[178:181], v189 offset:37888
	ds_read_b128 v[182:185], v189 offset:38912
	ds_read_b128 v[190:193], v189 offset:39936
	global_load_lds_dwordx4 v[244:245], off
	v_lshl_add_u64 v[246:247], s[10:11], 0, v[166:167]
	s_mov_b32 m0, s33
	ds_read_b128 v[194:197], v80 offset:16384
	ds_read_b128 v[198:201], v80 offset:17408
	ds_read_b128 v[202:205], v80 offset:18432
	ds_read_b128 v[206:209], v80 offset:19456
	global_load_lds_dwordx4 v[246:247], off
	s_waitcnt lgkmcnt(0)
	s_waitcnt vmcnt(8)
	s_barrier
	v_mfma_f32_16x16x32_bf16 v[126:129], v[130:133], v[146:149], v[126:129]
	v_mfma_f32_16x16x32_bf16 v[122:125], v[138:141], v[146:149], v[122:125]
	v_mfma_f32_16x16x32_bf16 v[118:121], v[130:133], v[154:157], v[118:121]
	v_mfma_f32_16x16x32_bf16 v[114:117], v[138:141], v[154:157], v[114:117]
	v_mfma_f32_16x16x32_bf16 v[110:113], v[130:133], v[174:177], v[110:113]
	v_mfma_f32_16x16x32_bf16 v[106:109], v[138:141], v[174:177], v[106:109]
	v_mfma_f32_16x16x32_bf16 v[102:105], v[130:133], v[182:185], v[102:105]
	v_mfma_f32_16x16x32_bf16 v[98:101], v[138:141], v[182:185], v[98:101]
	v_mfma_f32_16x16x32_bf16 v[126:129], v[134:137], v[150:153], v[126:129]
	v_mfma_f32_16x16x32_bf16 v[122:125], v[142:145], v[150:153], v[122:125]
	v_mfma_f32_16x16x32_bf16 v[118:121], v[134:137], v[158:161], v[118:121]
	v_mfma_f32_16x16x32_bf16 v[114:117], v[142:145], v[158:161], v[114:117]
	v_mfma_f32_16x16x32_bf16 v[110:113], v[134:137], v[178:181], v[110:113]
	v_mfma_f32_16x16x32_bf16 v[106:109], v[142:145], v[178:181], v[106:109]
	v_mfma_f32_16x16x32_bf16 v[102:105], v[134:137], v[190:193], v[102:105]
	v_mfma_f32_16x16x32_bf16 v[98:101], v[142:145], v[190:193], v[98:101]
	v_mfma_f32_16x16x32_bf16 v[60:63], v[194:197], v[146:149], v[60:63]
	v_mfma_f32_16x16x32_bf16 v[56:59], v[202:205], v[146:149], v[56:59]
	v_mfma_f32_16x16x32_bf16 v[52:55], v[194:197], v[154:157], v[52:55]
	v_mfma_f32_16x16x32_bf16 v[48:51], v[202:205], v[154:157], v[48:51]
	v_mfma_f32_16x16x32_bf16 v[44:47], v[194:197], v[174:177], v[44:47]
	v_mfma_f32_16x16x32_bf16 v[40:43], v[202:205], v[174:177], v[40:43]
	v_mfma_f32_16x16x32_bf16 v[36:39], v[194:197], v[182:185], v[36:39]
	v_mfma_f32_16x16x32_bf16 v[32:35], v[202:205], v[182:185], v[32:35]
	v_mfma_f32_16x16x32_bf16 v[60:63], v[198:201], v[150:153], v[60:63]
	v_mfma_f32_16x16x32_bf16 v[56:59], v[206:209], v[150:153], v[56:59]
	v_mfma_f32_16x16x32_bf16 v[52:55], v[198:201], v[158:161], v[52:55]
	v_mfma_f32_16x16x32_bf16 v[48:51], v[206:209], v[158:161], v[48:51]
	v_mfma_f32_16x16x32_bf16 v[44:47], v[198:201], v[178:181], v[44:47]
	v_mfma_f32_16x16x32_bf16 v[40:43], v[206:209], v[178:181], v[40:43]
	v_mfma_f32_16x16x32_bf16 v[36:39], v[198:201], v[190:193], v[36:39]
	v_mfma_f32_16x16x32_bf16 v[32:35], v[206:209], v[190:193], v[32:35]
	s_add_i32 s10, 0, 0x1c000
	s_add_i32 s11, s12, s14
	s_barrier
; #define PG8_STAGE(bufoff, gbase, voff) do { _Pragma("unroll") for (int _i = 0; _i < 2; ++_i) \
;     __builtin_amdgcn_global_load_lds((const unsigned*)((const char*)(gbase) + (voff)[_i]), (LAS unsigned*)(lds + (bufoff) + ldsw + _i * 8192), 16, 0, 0); } while (0)
; #define PG8_LDA(dst, b, h) do { _Pragma("unroll") for (int m = 0; m < 4; ++m) _Pragma("unroll") for (int k = 0; k < 2; ++k) dst[m][k] = *(const LAS bf16x8*)(lds + PG8_SA(b, h) + aoff + m * 2048 + k * 1024); } while (0)
; #define PG8_MMA(ai, bj, At, Bt) do { __builtin_amdgcn_s_setprio(1); _Pragma("unroll") for (int m = 0; m < 4; ++m) _Pragma("unroll") for (int n = 0; n < 2; ++n) _Pragma("unroll") for (int k = 0; k < 2; ++k) \
;     acc[ai][bj][m][n] = __builtin_amdgcn_mfma_f32_16x16x32_bf16(Bt[n][k], At[m][k], acc[ai][bj][m][n], 0, 0, 0); __builtin_amdgcn_s_setprio(0); } while (0)
; #define PG8_WAIT_V(n) asm volatile("s_waitcnt vmcnt(" #n ")" ::: "memory")
; #define PG8_WAIT_L(n) asm volatile("s_waitcnt lgkmcnt(" #n ")" ::: "memory")
; #define PG8_BAR __builtin_amdgcn_s_barrier()
; #define PG8_SCHED __builtin_amdgcn_sched_barrier(0)
; template <class Epi>
; __device__ __forceinline__ void gemm_phase(LAS unsigned char* lds, const Gemm g, const StaticOrder& S, const Epi& E) {
;     ...
;       PG8_LDA(At, 1, 1); PG8_STAGE(PG8_SA(1, 0), a3, voffA);
;       PG8_BAR; PG8_WAIT_L(0); PG8_MMA(1, 0, At, B0); PG8_BAR; PG8_SCHED;
;       PG8_STAGE(PG8_SB(1, 1), b3 + hstep, voffB);
;       PG8_WAIT_V(6); PG8_BAR; PG8_MMA(1, 1, At, B1); PG8_BAR;
;     }
	ds_read_b128 v[146:149], v189 offset:49152
	ds_read_b128 v[150:153], v189 offset:50176
	ds_read_b128 v[154:157], v189 offset:51200
	ds_read_b128 v[158:161], v189 offset:52224
	ds_read_b128 v[174:177], v189 offset:53248
	ds_read_b128 v[178:181], v189 offset:54272
	ds_read_b128 v[182:185], v189 offset:55296
	ds_read_b128 v[190:193], v189 offset:56320
	v_lshl_add_u64 v[210:211], v[210:211], 0, s[90:91]
	s_mov_b32 m0, s11
	v_lshl_add_u64 v[212:213], v[212:213], 0, s[90:91]
	global_load_lds_dwordx4 v[210:211], off
	s_add_i32 m0, s11, 0x2000
	v_lshl_add_u64 v[216:217], v[216:217], 0, s[90:91]
	global_load_lds_dwordx4 v[212:213], off
	s_mov_b32 m0, s29
	v_lshl_add_u64 v[232:233], v[232:233], 0, s[90:91]
	global_load_lds_dwordx4 v[216:217], off
	s_mov_b32 m0, s20
	s_add_i32 s10, s10, s14
	global_load_lds_dwordx4 v[232:233], off
	v_lshl_add_u64 v[244:245], v[236:237], 0, s[90:91]
	s_mov_b32 m0, s10
	v_lshl_add_u64 v[246:247], v[242:243], 0, s[90:91]
	global_load_lds_dwordx4 v[244:245], off
	s_add_i32 m0, s10, 0x2000
	s_nop 0
	global_load_lds_dwordx4 v[246:247], off
	s_waitcnt lgkmcnt(0)
	s_waitcnt vmcnt(8)
	s_barrier
	v_mfma_f32_16x16x32_bf16 v[94:97], v[130:133], v[146:149], v[94:97]
	v_mfma_f32_16x16x32_bf16 v[90:93], v[138:141], v[146:149], v[90:93]
	v_mfma_f32_16x16x32_bf16 v[86:89], v[130:133], v[154:157], v[86:89]
	v_mfma_f32_16x16x32_bf16 v[82:85], v[138:141], v[154:157], v[82:85]
	v_mfma_f32_16x16x32_bf16 v[76:79], v[130:133], v[174:177], v[76:79]
	v_mfma_f32_16x16x32_bf16 v[72:75], v[138:141], v[174:177], v[72:75]
	v_mfma_f32_16x16x32_bf16 v[68:71], v[130:133], v[182:185], v[68:71]
	v_mfma_f32_16x16x32_bf16 v[64:67], v[138:141], v[182:185], v[64:67]
	v_mfma_f32_16x16x32_bf16 v[94:97], v[134:137], v[150:153], v[94:97]
	v_mfma_f32_16x16x32_bf16 v[90:93], v[142:145], v[150:153], v[90:93]
	v_mfma_f32_16x16x32_bf16 v[86:89], v[134:137], v[158:161], v[86:89]
	v_mfma_f32_16x16x32_bf16 v[82:85], v[142:145], v[158:161], v[82:85]
	v_mfma_f32_16x16x32_bf16 v[76:79], v[134:137], v[178:181], v[76:79]
	v_mfma_f32_16x16x32_bf16 v[72:75], v[142:145], v[178:181], v[72:75]
	v_mfma_f32_16x16x32_bf16 v[68:71], v[134:137], v[190:193], v[68:71]
	v_mfma_f32_16x16x32_bf16 v[64:67], v[142:145], v[190:193], v[64:67]
	v_mfma_f32_16x16x32_bf16 v[28:31], v[194:197], v[146:149], v[28:31]
	v_mfma_f32_16x16x32_bf16 v[24:27], v[202:205], v[146:149], v[24:27]
	v_mfma_f32_16x16x32_bf16 v[20:23], v[194:197], v[154:157], v[20:23]
	v_mfma_f32_16x16x32_bf16 v[16:19], v[202:205], v[154:157], v[16:19]
	v_mfma_f32_16x16x32_bf16 v[12:15], v[194:197], v[174:177], v[12:15]
	v_mfma_f32_16x16x32_bf16 v[8:11], v[202:205], v[174:177], v[8:11]
	v_mfma_f32_16x16x32_bf16 v[4:7], v[194:197], v[182:185], v[4:7]
	v_mfma_f32_16x16x32_bf16 v[0:3], v[202:205], v[182:185], v[0:3]
	v_mfma_f32_16x16x32_bf16 v[28:31], v[198:201], v[150:153], v[28:31]
	v_mfma_f32_16x16x32_bf16 v[24:27], v[206:209], v[150:153], v[24:27]
	v_mfma_f32_16x16x32_bf16 v[20:23], v[198:201], v[158:161], v[20:23]
	v_mfma_f32_16x16x32_bf16 v[16:19], v[206:209], v[158:161], v[16:19]
	v_mfma_f32_16x16x32_bf16 v[12:15], v[198:201], v[178:181], v[12:15]
	v_mfma_f32_16x16x32_bf16 v[8:11], v[206:209], v[178:181], v[8:11]
	v_mfma_f32_16x16x32_bf16 v[4:7], v[198:201], v[190:193], v[4:7]
	v_mfma_f32_16x16x32_bf16 v[0:3], v[206:209], v[190:193], v[0:3]
	s_add_u32 s74, s74, 0x100
	s_addc_u32 s75, s75, 0
	s_add_u32 s0, s0, 0x100
	s_addc_u32 s1, s1, 0
	s_cmp_ge_u32 s76, s2
	s_mov_b32 s10, s76
	s_barrier
	s_cbranch_scc1 .Lkdone
.LBB0_56:
	s_add_i32 s76, s10, 2
	s_add_u32 s12, s0, 0x80
	s_addc_u32 s11, s1, 0
	s_add_i32 s77, 0, 0x10000
	v_add_u32_e32 v80, s77, v187
	ds_read_b128 v[130:133], v80
	ds_read_b128 v[134:137], v80 offset:1024
	ds_read_b128 v[138:141], v80 offset:2048
	ds_read_b128 v[142:145], v80 offset:3072
	s_cmp_eq_u32 s21, s10
	s_cselect_b32 s10, s18, s12
	s_cselect_b32 s11, s19, s11
	s_cselect_b32 s13, s17, s75
	s_cselect_b32 s12, s16, s74
	v_lshl_add_u64 v[244:245], s[0:1], 0, v[172:173]
	s_add_i32 m0, s15, 0xc000
	ds_read_b128 v[146:149], v189
	ds_read_b128 v[150:153], v189 offset:1024
	ds_read_b128 v[154:157], v189 offset:2048
	ds_read_b128 v[158:161], v189 offset:3072
	ds_read_b128 v[174:177], v189 offset:4096
	ds_read_b128 v[178:181], v189 offset:5120
	ds_read_b128 v[182:185], v189 offset:6144
	ds_read_b128 v[190:193], v189 offset:7168
	global_load_lds_dwordx4 v[244:245], off
	v_lshl_add_u64 v[246:247], s[0:1], 0, v[170:171]
	s_add_i32 m0, s15, 0xe000
	ds_read_b128 v[194:197], v80 offset:16384
	ds_read_b128 v[198:201], v80 offset:17408
	ds_read_b128 v[202:205], v80 offset:18432
	ds_read_b128 v[206:209], v80 offset:19456
	global_load_lds_dwordx4 v[246:247], off
	s_waitcnt lgkmcnt(0)
	s_waitcnt vmcnt(8)
	s_barrier
; #define PG8_STAGE(bufoff, gbase, voff) do { _Pragma("unroll") for (int _i = 0; _i < 2; ++_i) \
;     __builtin_amdgcn_global_load_lds((const unsigned*)((const char*)(gbase) + (voff)[_i]), (LAS unsigned*)(lds + (bufoff) + ldsw + _i * 8192), 16, 0, 0); } while (0)
; #define PG8_LDA(dst, b, h) do { _Pragma("unroll") for (int m = 0; m < 4; ++m) _Pragma("unroll") for (int k = 0; k < 2; ++k) dst[m][k] = *(const LAS bf16x8*)(lds + PG8_SA(b, h) + aoff + m * 2048 + k * 1024); } while (0)
; #define PG8_LDB(dst, b, h) do { _Pragma("unroll") for (int n = 0; n < 2; ++n) _Pragma("unroll") for (int k = 0; k < 2; ++k) dst[n][k] = *(const LAS bf16x8*)(lds + PG8_SB(b, h) + boff + n * 2048 + k * 1024); } while (0)
; #define PG8_MMA(ai, bj, At, Bt) do { __builtin_amdgcn_s_setprio(1); _Pragma("unroll") for (int m = 0; m < 4; ++m) _Pragma("unroll") for (int n = 0; n < 2; ++n) _Pragma("unroll") for (int k = 0; k < 2; ++k) \
;     acc[ai][bj][m][n] = __builtin_amdgcn_mfma_f32_16x16x32_bf16(Bt[n][k], At[m][k], acc[ai][bj][m][n], 0, 0, 0); __builtin_amdgcn_s_setprio(0); } while (0)
; #define PG8_WAIT_V(n) asm volatile("s_waitcnt vmcnt(" #n ")" ::: "memory")
; #define PG8_WAIT_L(n) asm volatile("s_waitcnt lgkmcnt(" #n ")" ::: "memory")
; #define PG8_BAR __builtin_amdgcn_s_barrier()
; #define PG8_SCHED __builtin_amdgcn_sched_barrier(0)
; template <class Epi>
; __device__ __forceinline__ void gemm_phase(LAS unsigned char* lds, const Gemm g, const StaticOrder& S, const Epi& E) {
;     ...
;       PG8_LDB(B0, 0, 0); PG8_SCHED; PG8_LDA(At, 0, 0); PG8_STAGE(PG8_SA(1, 1), a1 + hstep, voffA);
;       PG8_WAIT_L(8); PG8_BAR; PG8_WAIT_L(0); PG8_MMA(0, 0, At, B0); PG8_BAR; PG8_SCHED;
;       PG8_LDB(B1, 0, 1); PG8_STAGE(PG8_SB(0, 0), b2, voffB);
;       PG8_BAR; PG8_WAIT_L(0); PG8_MMA(0, 1, At, B1); PG8_BAR;
;       PG8_LDA(At, 0, 1); PG8_STAGE(PG8_SA(0, 0), a2, voffA);
;       PG8_BAR; PG8_WAIT_L(0); PG8_MMA(1, 0, At, B0); PG8_BAR; PG8_SCHED;
;       PG8_STAGE(PG8_SB(0, 1), b2 + hstep, voffB);
;       PG8_WAIT_V(6); PG8_BAR; PG8_MMA(1, 1, At, B1); PG8_BAR;
	v_mfma_f32_16x16x32_bf16 v[126:129], v[130:133], v[146:149], v[126:129]
	v_mfma_f32_16x16x32_bf16 v[122:125], v[138:141], v[146:149], v[122:125]
	v_mfma_f32_16x16x32_bf16 v[118:121], v[130:133], v[154:157], v[118:121]
	v_mfma_f32_16x16x32_bf16 v[114:117], v[138:141], v[154:157], v[114:117]
	v_mfma_f32_16x16x32_bf16 v[110:113], v[130:133], v[174:177], v[110:113]
	v_mfma_f32_16x16x32_bf16 v[106:109], v[138:141], v[174:177], v[106:109]
	v_mfma_f32_16x16x32_bf16 v[102:105], v[130:133], v[182:185], v[102:105]
	v_mfma_f32_16x16x32_bf16 v[98:101], v[138:141], v[182:185], v[98:101]
	v_mfma_f32_16x16x32_bf16 v[126:129], v[134:137], v[150:153], v[126:129]
	v_mfma_f32_16x16x32_bf16 v[122:125], v[142:145], v[150:153], v[122:125]
	v_mfma_f32_16x16x32_bf16 v[118:121], v[134:137], v[158:161], v[118:121]
	v_mfma_f32_16x16x32_bf16 v[114:117], v[142:145], v[158:161], v[114:117]
	v_mfma_f32_16x16x32_bf16 v[110:113], v[134:137], v[178:181], v[110:113]
	v_mfma_f32_16x16x32_bf16 v[106:109], v[142:145], v[178:181], v[106:109]
	v_mfma_f32_16x16x32_bf16 v[102:105], v[134:137], v[190:193], v[102:105]
	v_mfma_f32_16x16x32_bf16 v[98:101], v[142:145], v[190:193], v[98:101]
	v_mfma_f32_16x16x32_bf16 v[60:63], v[194:197], v[146:149], v[60:63]
	v_mfma_f32_16x16x32_bf16 v[56:59], v[202:205], v[146:149], v[56:59]
	v_mfma_f32_16x16x32_bf16 v[52:55], v[194:197], v[154:157], v[52:55]
	v_mfma_f32_16x16x32_bf16 v[48:51], v[202:205], v[154:157], v[48:51]
	v_mfma_f32_16x16x32_bf16 v[44:47], v[194:197], v[174:177], v[44:47]
	v_mfma_f32_16x16x32_bf16 v[40:43], v[202:205], v[174:177], v[40:43]
	v_mfma_f32_16x16x32_bf16 v[36:39], v[194:197], v[182:185], v[36:39]
	v_mfma_f32_16x16x32_bf16 v[32:35], v[202:205], v[182:185], v[32:35]
	v_mfma_f32_16x16x32_bf16 v[60:63], v[198:201], v[150:153], v[60:63]
	v_mfma_f32_16x16x32_bf16 v[56:59], v[206:209], v[150:153], v[56:59]
	v_mfma_f32_16x16x32_bf16 v[52:55], v[198:201], v[158:161], v[52:55]
	v_mfma_f32_16x16x32_bf16 v[48:51], v[206:209], v[158:161], v[48:51]
	v_mfma_f32_16x16x32_bf16 v[44:47], v[198:201], v[178:181], v[44:47]
	v_mfma_f32_16x16x32_bf16 v[40:43], v[206:209], v[178:181], v[40:43]
	v_mfma_f32_16x16x32_bf16 v[36:39], v[198:201], v[190:193], v[36:39]
	v_mfma_f32_16x16x32_bf16 v[32:35], v[206:209], v[190:193], v[32:35]
	s_add_i32 s78, 0, 0x14000
	s_add_i32 s77, s77, s14
	s_barrier
	ds_read_b128 v[146:149], v189 offset:16384
	ds_read_b128 v[150:153], v189 offset:17408
	ds_read_b128 v[154:157], v189 offset:18432
	ds_read_b128 v[158:161], v189 offset:19456
	ds_read_b128 v[174:177], v189 offset:20480
	ds_read_b128 v[178:181], v189 offset:21504
	ds_read_b128 v[182:185], v189 offset:22528
	ds_read_b128 v[190:193], v189 offset:23552
	v_lshl_add_u64 v[210:211], s[12:13], 0, v[164:165]
	s_mov_b32 m0, s77
	v_lshl_add_u64 v[212:213], s[12:13], 0, v[168:169]
	global_load_lds_dwordx4 v[210:211], off
	s_add_i32 m0, s77, 0x2000
	v_lshl_add_u64 v[216:217], s[10:11], 0, v[162:163]
	global_load_lds_dwordx4 v[212:213], off
	s_mov_b32 m0, s15
	v_lshl_add_u64 v[232:233], s[10:11], 0, v[166:167]
	global_load_lds_dwordx4 v[216:217], off
	s_mov_b32 m0, s84
	s_add_u32 s12, s12, s64
	s_addc_u32 s13, s13, 0
	global_load_lds_dwordx4 v[232:233], off
	s_add_i32 s77, s78, s14
	v_lshl_add_u64 v[236:237], s[12:13], 0, v[164:165]
	s_mov_b32 m0, s77
	v_lshl_add_u64 v[242:243], s[12:13], 0, v[168:169]
	global_load_lds_dwordx4 v[236:237], off
	s_add_i32 m0, s77, 0x2000
	global_load_lds_dwordx4 v[242:243], off
	s_waitcnt lgkmcnt(0)
	s_waitcnt vmcnt(8)
	s_barrier
	v_mfma_f32_16x16x32_bf16 v[94:97], v[130:133], v[146:149], v[94:97]
	v_mfma_f32_16x16x32_bf16 v[90:93], v[138:141], v[146:149], v[90:93]
	v_mfma_f32_16x16x32_bf16 v[86:89], v[130:133], v[154:157], v[86:89]
	v_mfma_f32_16x16x32_bf16 v[82:85], v[138:141], v[154:157], v[82:85]
	v_mfma_f32_16x16x32_bf16 v[76:79], v[130:133], v[174:177], v[76:79]
	v_mfma_f32_16x16x32_bf16 v[72:75], v[138:141], v[174:177], v[72:75]
	v_mfma_f32_16x16x32_bf16 v[68:71], v[130:133], v[182:185], v[68:71]
	v_mfma_f32_16x16x32_bf16 v[64:67], v[138:141], v[182:185], v[64:67]
	v_mfma_f32_16x16x32_bf16 v[94:97], v[134:137], v[150:153], v[94:97]
	v_mfma_f32_16x16x32_bf16 v[90:93], v[142:145], v[150:153], v[90:93]
	v_mfma_f32_16x16x32_bf16 v[86:89], v[134:137], v[158:161], v[86:89]
	v_mfma_f32_16x16x32_bf16 v[82:85], v[142:145], v[158:161], v[82:85]
	v_mfma_f32_16x16x32_bf16 v[76:79], v[134:137], v[178:181], v[76:79]
	v_mfma_f32_16x16x32_bf16 v[72:75], v[142:145], v[178:181], v[72:75]
	v_mfma_f32_16x16x32_bf16 v[68:71], v[134:137], v[190:193], v[68:71]
	v_mfma_f32_16x16x32_bf16 v[64:67], v[142:145], v[190:193], v[64:67]
	v_mfma_f32_16x16x32_bf16 v[28:31], v[194:197], v[146:149], v[28:31]
	v_mfma_f32_16x16x32_bf16 v[24:27], v[202:205], v[146:149], v[24:27]
	v_mfma_f32_16x16x32_bf16 v[20:23], v[194:197], v[154:157], v[20:23]
	v_mfma_f32_16x16x32_bf16 v[16:19], v[202:205], v[154:157], v[16:19]
	v_mfma_f32_16x16x32_bf16 v[12:15], v[194:197], v[174:177], v[12:15]
	v_mfma_f32_16x16x32_bf16 v[8:11], v[202:205], v[174:177], v[8:11]
	v_mfma_f32_16x16x32_bf16 v[4:7], v[194:197], v[182:185], v[4:7]
	v_mfma_f32_16x16x32_bf16 v[0:3], v[202:205], v[182:185], v[0:3]
	v_mfma_f32_16x16x32_bf16 v[28:31], v[198:201], v[150:153], v[28:31]
	v_mfma_f32_16x16x32_bf16 v[24:27], v[206:209], v[150:153], v[24:27]
	v_mfma_f32_16x16x32_bf16 v[20:23], v[198:201], v[158:161], v[20:23]
	v_mfma_f32_16x16x32_bf16 v[16:19], v[206:209], v[158:161], v[16:19]
	v_mfma_f32_16x16x32_bf16 v[12:15], v[198:201], v[178:181], v[12:15]
	v_mfma_f32_16x16x32_bf16 v[8:11], v[206:209], v[178:181], v[8:11]
	v_mfma_f32_16x16x32_bf16 v[4:7], v[198:201], v[190:193], v[4:7]
	v_mfma_f32_16x16x32_bf16 v[0:3], v[206:209], v[190:193], v[0:3]
	s_add_i32 s12, 0, 0x18000
	v_add_u32_e32 v80, s12, v187
	s_barrier
; #define PG8_STAGE(bufoff, gbase, voff) do { _Pragma("unroll") for (int _i = 0; _i < 2; ++_i) \
;     __builtin_amdgcn_global_load_lds((const unsigned*)((const char*)(gbase) + (voff)[_i]), (LAS unsigned*)(lds + (bufoff) + ldsw + _i * 8192), 16, 0, 0); } while (0)
; #define PG8_LDA(dst, b, h) do { _Pragma("unroll") for (int m = 0; m < 4; ++m) _Pragma("unroll") for (int k = 0; k < 2; ++k) dst[m][k] = *(const LAS bf16x8*)(lds + PG8_SA(b, h) + aoff + m * 2048 + k * 1024); } while (0)
; #define PG8_LDB(dst, b, h) do { _Pragma("unroll") for (int n = 0; n < 2; ++n) _Pragma("unroll") for (int k = 0; k < 2; ++k) dst[n][k] = *(const LAS bf16x8*)(lds + PG8_SB(b, h) + boff + n * 2048 + k * 1024); } while (0)
; #define PG8_MMA(ai, bj, At, Bt) do { __builtin_amdgcn_s_setprio(1); _Pragma("unroll") for (int m = 0; m < 4; ++m) _Pragma("unroll") for (int n = 0; n < 2; ++n) _Pragma("unroll") for (int k = 0; k < 2; ++k) \
;     acc[ai][bj][m][n] = __builtin_amdgcn_mfma_f32_16x16x32_bf16(Bt[n][k], At[m][k], acc[ai][bj][m][n], 0, 0, 0); __builtin_amdgcn_s_setprio(0); } while (0)
; #define PG8_WAIT_V(n) asm volatile("s_waitcnt vmcnt(" #n ")" ::: "memory")
; #define PG8_WAIT_L(n) asm volatile("s_waitcnt lgkmcnt(" #n ")" ::: "memory")
; #define PG8_BAR __builtin_amdgcn_s_barrier()
; #define PG8_SCHED __builtin_amdgcn_sched_barrier(0)
; template <class Epi>
; __device__ __forceinline__ void gemm_phase(LAS unsigned char* lds, const Gemm g, const StaticOrder& S, const Epi& E) {
;     ...
;       PG8_LDB(B0, 1, 0); PG8_SCHED; PG8_LDA(At, 1, 0); PG8_STAGE(PG8_SA(0, 1), a2 + hstep, voffA);
;       PG8_WAIT_L(8); PG8_BAR; PG8_WAIT_L(0); PG8_MMA(0, 0, At, B0); PG8_BAR; PG8_SCHED;
;       PG8_LDB(B1, 1, 1); PG8_STAGE(PG8_SB(1, 0), b3, voffB);
;       PG8_BAR; PG8_WAIT_L(0); PG8_MMA(0, 1, At, B1); PG8_BAR;
;       PG8_LDA(At, 1, 1); PG8_STAGE(PG8_SA(1, 0), a3, voffA);
;       PG8_BAR; PG8_WAIT_L(0); PG8_MMA(1, 0, At, B0); PG8_BAR; PG8_SCHED;
;       PG8_STAGE(PG8_SB(1, 1), b3 + hstep, voffB);
;       PG8_WAIT_V(6); PG8_BAR; PG8_MMA(1, 1, At, B1); PG8_BAR;
	ds_read_b128 v[130:133], v80
	ds_read_b128 v[134:137], v80 offset:1024
	ds_read_b128 v[138:141], v80 offset:2048
	ds_read_b128 v[142:145], v80 offset:3072
	s_add_u32 s10, s10, s64
	s_addc_u32 s11, s11, 0
	s_mov_b32 m0, s99
	v_lshl_add_u64 v[244:245], s[10:11], 0, v[162:163]
	ds_read_b128 v[146:149], v189 offset:32768
	ds_read_b128 v[150:153], v189 offset:33792
	ds_read_b128 v[154:157], v189 offset:34816
	ds_read_b128 v[158:161], v189 offset:35840
	ds_read_b128 v[174:177], v189 offset:36864
	ds_read_b128 v[178:181], v189 offset:37888
	ds_read_b128 v[182:185], v189 offset:38912
	ds_read_b128 v[190:193], v189 offset:39936
	global_load_lds_dwordx4 v[244:245], off
	v_lshl_add_u64 v[246:247], s[10:11], 0, v[166:167]
	s_mov_b32 m0, s33
	ds_read_b128 v[194:197], v80 offset:16384
	ds_read_b128 v[198:201], v80 offset:17408
	ds_read_b128 v[202:205], v80 offset:18432
	ds_read_b128 v[206:209], v80 offset:19456
	global_load_lds_dwordx4 v[246:247], off
	s_waitcnt lgkmcnt(0)
	s_waitcnt vmcnt(8)
	s_barrier
	v_mfma_f32_16x16x32_bf16 v[126:129], v[130:133], v[146:149], v[126:129]
	v_mfma_f32_16x16x32_bf16 v[122:125], v[138:141], v[146:149], v[122:125]
	v_mfma_f32_16x16x32_bf16 v[118:121], v[130:133], v[154:157], v[118:121]
	v_mfma_f32_16x16x32_bf16 v[114:117], v[138:141], v[154:157], v[114:117]
	v_mfma_f32_16x16x32_bf16 v[110:113], v[130:133], v[174:177], v[110:113]
	v_mfma_f32_16x16x32_bf16 v[106:109], v[138:141], v[174:177], v[106:109]
	v_mfma_f32_16x16x32_bf16 v[102:105], v[130:133], v[182:185], v[102:105]
	v_mfma_f32_16x16x32_bf16 v[98:101], v[138:141], v[182:185], v[98:101]
	v_mfma_f32_16x16x32_bf16 v[126:129], v[134:137], v[150:153], v[126:129]
	v_mfma_f32_16x16x32_bf16 v[122:125], v[142:145], v[150:153], v[122:125]
	v_mfma_f32_16x16x32_bf16 v[118:121], v[134:137], v[158:161], v[118:121]
	v_mfma_f32_16x16x32_bf16 v[114:117], v[142:145], v[158:161], v[114:117]
	v_mfma_f32_16x16x32_bf16 v[110:113], v[134:137], v[178:181], v[110:113]
	v_mfma_f32_16x16x32_bf16 v[106:109], v[142:145], v[178:181], v[106:109]
	v_mfma_f32_16x16x32_bf16 v[102:105], v[134:137], v[190:193], v[102:105]
	v_mfma_f32_16x16x32_bf16 v[98:101], v[142:145], v[190:193], v[98:101]
	v_mfma_f32_16x16x32_bf16 v[60:63], v[194:197], v[146:149], v[60:63]
	v_mfma_f32_16x16x32_bf16 v[56:59], v[202:205], v[146:149], v[56:59]
	v_mfma_f32_16x16x32_bf16 v[52:55], v[194:197], v[154:157], v[52:55]
	v_mfma_f32_16x16x32_bf16 v[48:51], v[202:205], v[154:157], v[48:51]
	v_mfma_f32_16x16x32_bf16 v[44:47], v[194:197], v[174:177], v[44:47]
	v_mfma_f32_16x16x32_bf16 v[40:43], v[202:205], v[174:177], v[40:43]
	v_mfma_f32_16x16x32_bf16 v[36:39], v[194:197], v[182:185], v[36:39]
	v_mfma_f32_16x16x32_bf16 v[32:35], v[202:205], v[182:185], v[32:35]
	v_mfma_f32_16x16x32_bf16 v[60:63], v[198:201], v[150:153], v[60:63]
	v_mfma_f32_16x16x32_bf16 v[56:59], v[206:209], v[150:153], v[56:59]
	v_mfma_f32_16x16x32_bf16 v[52:55], v[198:201], v[158:161], v[52:55]
	v_mfma_f32_16x16x32_bf16 v[48:51], v[206:209], v[158:161], v[48:51]
	v_mfma_f32_16x16x32_bf16 v[44:47], v[198:201], v[178:181], v[44:47]
	v_mfma_f32_16x16x32_bf16 v[40:43], v[206:209], v[178:181], v[40:43]
	v_mfma_f32_16x16x32_bf16 v[36:39], v[198:201], v[190:193], v[36:39]
	v_mfma_f32_16x16x32_bf16 v[32:35], v[206:209], v[190:193], v[32:35]
	s_add_i32 s10, 0, 0x1c000
	s_add_i32 s11, s12, s14
	s_barrier
	ds_read_b128 v[146:149], v189 offset:49152
	ds_read_b128 v[150:153], v189 offset:50176
	ds_read_b128 v[154:157], v189 offset:51200
	ds_read_b128 v[158:161], v189 offset:52224
	ds_read_b128 v[174:177], v189 offset:53248
	ds_read_b128 v[178:181], v189 offset:54272
	ds_read_b128 v[182:185], v189 offset:55296
	ds_read_b128 v[190:193], v189 offset:56320
	v_lshl_add_u64 v[210:211], v[210:211], 0, s[90:91]
	s_mov_b32 m0, s11
	v_lshl_add_u64 v[212:213], v[212:213], 0, s[90:91]
	global_load_lds_dwordx4 v[210:211], off
	s_add_i32 m0, s11, 0x2000
	v_lshl_add_u64 v[216:217], v[216:217], 0, s[90:91]
	global_load_lds_dwordx4 v[212:213], off
	s_mov_b32 m0, s29
	v_lshl_add_u64 v[232:233], v[232:233], 0, s[90:91]
	global_load_lds_dwordx4 v[216:217], off
	s_mov_b32 m0, s20
	s_add_i32 s10, s10, s14
	global_load_lds_dwordx4 v[232:233], off
	v_lshl_add_u64 v[244:245], v[236:237], 0, s[90:91]
	s_mov_b32 m0, s10
	v_lshl_add_u64 v[246:247], v[242:243], 0, s[90:91]
	global_load_lds_dwordx4 v[244:245], off
	s_add_i32 m0, s10, 0x2000
	s_nop 0
	global_load_lds_dwordx4 v[246:247], off
	s_waitcnt lgkmcnt(0)
	s_waitcnt vmcnt(8)
	s_barrier
	v_mfma_f32_16x16x32_bf16 v[94:97], v[130:133], v[146:149], v[94:97]
	v_mfma_f32_16x16x32_bf16 v[90:93], v[138:141], v[146:149], v[90:93]
	v_mfma_f32_16x16x32_bf16 v[86:89], v[130:133], v[154:157], v[86:89]
	v_mfma_f32_16x16x32_bf16 v[82:85], v[138:141], v[154:157], v[82:85]
	v_mfma_f32_16x16x32_bf16 v[76:79], v[130:133], v[174:177], v[76:79]
	v_mfma_f32_16x16x32_bf16 v[72:75], v[138:141], v[174:177], v[72:75]
	v_mfma_f32_16x16x32_bf16 v[68:71], v[130:133], v[182:185], v[68:71]
	v_mfma_f32_16x16x32_bf16 v[64:67], v[138:141], v[182:185], v[64:67]
	v_mfma_f32_16x16x32_bf16 v[94:97], v[134:137], v[150:153], v[94:97]
	v_mfma_f32_16x16x32_bf16 v[90:93], v[142:145], v[150:153], v[90:93]
	v_mfma_f32_16x16x32_bf16 v[86:89], v[134:137], v[158:161], v[86:89]
	v_mfma_f32_16x16x32_bf16 v[82:85], v[142:145], v[158:161], v[82:85]
	v_mfma_f32_16x16x32_bf16 v[76:79], v[134:137], v[178:181], v[76:79]
	v_mfma_f32_16x16x32_bf16 v[72:75], v[142:145], v[178:181], v[72:75]
	v_mfma_f32_16x16x32_bf16 v[68:71], v[134:137], v[190:193], v[68:71]
	v_mfma_f32_16x16x32_bf16 v[64:67], v[142:145], v[190:193], v[64:67]
	v_mfma_f32_16x16x32_bf16 v[28:31], v[194:197], v[146:149], v[28:31]
	v_mfma_f32_16x16x32_bf16 v[24:27], v[202:205], v[146:149], v[24:27]
	v_mfma_f32_16x16x32_bf16 v[20:23], v[194:197], v[154:157], v[20:23]
	v_mfma_f32_16x16x32_bf16 v[16:19], v[202:205], v[154:157], v[16:19]
	v_mfma_f32_16x16x32_bf16 v[12:15], v[194:197], v[174:177], v[12:15]
	v_mfma_f32_16x16x32_bf16 v[8:11], v[202:205], v[174:177], v[8:11]
	v_mfma_f32_16x16x32_bf16 v[4:7], v[194:197], v[182:185], v[4:7]
	v_mfma_f32_16x16x32_bf16 v[0:3], v[202:205], v[182:185], v[0:3]
	v_mfma_f32_16x16x32_bf16 v[28:31], v[198:201], v[150:153], v[28:31]
	v_mfma_f32_16x16x32_bf16 v[24:27], v[206:209], v[150:153], v[24:27]
	v_mfma_f32_16x16x32_bf16 v[20:23], v[198:201], v[158:161], v[20:23]
	v_mfma_f32_16x16x32_bf16 v[16:19], v[206:209], v[158:161], v[16:19]
	v_mfma_f32_16x16x32_bf16 v[12:15], v[198:201], v[178:181], v[12:15]
	v_mfma_f32_16x16x32_bf16 v[8:11], v[206:209], v[178:181], v[8:11]
	v_mfma_f32_16x16x32_bf16 v[4:7], v[198:201], v[190:193], v[4:7]
	v_mfma_f32_16x16x32_bf16 v[0:3], v[206:209], v[190:193], v[0:3]
	s_add_u32 s74, s74, 0x100
	s_addc_u32 s75, s75, 0
	s_add_u32 s0, s0, 0x100
	s_addc_u32 s1, s1, 0
	s_cmp_ge_u32 s76, s2
	s_mov_b32 s10, s76
	s_barrier
	s_cbranch_scc0 .LBB0_56
; __device__ __forceinline__ float lo16(unsigned v) { return __uint_as_float(v << 16); }
; __device__ __forceinline__ float hi16(unsigned v) { return __uint_as_float(v & 0xffff0000u); }
;   __device__ __forceinline__ void operator()(const f32x4 (&acc)[2][2][4][2], const pg8::Unit& u, int wr, int wc, int fr, int fq) const {
;     unsigned char* ws = wsl;
;     const int prow = u.swap ? u.pn : u.pm, pcol = u.swap ? u.pm : u.pn;
;     const int row0 = prow * 256 + wr * 64 + fr, col0 = pcol * 256 + wc * 32 + 8 * fq;
;     ...
;       float* xo = P->out + (size_t)slice * TS * DM; const u16* x2b = (const u16*)(ws + O_X2B) + (size_t)slice * TS * DM;
; #pragma unroll
;       for (int ai = 0; ai < 2; ++ai) {
;         u32x4 xv[4][2];
; #pragma unroll
;         for (int m = 0; m < 4; ++m)
; #pragma unroll
;           for (int bj = 0; bj < 2; ++bj) xv[m][bj] = *(const u32x4*)(x2b + (size_t)(row0 + ai * 128 + m * 16) * DM + col0 + bj * 128);
;         __builtin_amdgcn_sched_barrier(0);
; #pragma unroll
;         for (int m = 0; m < 4; ++m) {
;           const int row = row0 + ai * 128 + m * 16;
; #pragma unroll
;           for (int bj = 0; bj < 2; ++bj) {
;             float* d = xo + (size_t)row * DM + col0 + bj * 128;
;             const u32x4 x4 = xv[m][bj];
;             f32x4 o0 = acc[ai][bj][m][0], o1 = acc[ai][bj][m][1];
;             o0[0] += lo16(x4.x); o0[1] += hi16(x4.x); o0[2] += lo16(x4.y); o0[3] += hi16(x4.y); o1[0] += lo16(x4.z); o1[1] += hi16(x4.z); o1[2] += lo16(x4.w); o1[3] += hi16(x4.w);
;             *(f32x4*)d = o0; *(f32x4*)(d + 4) = o1;
;           }
;         }
.Lkdone:
	s_cmp_lg_u32 s71, 0
	s_cselect_b64 s[0:1], -1, 0
	s_cmp_eq_u32 s71, 0
	s_cselect_b32 s10, s73, s72
	s_cselect_b32 s11, s72, s73
	s_lshl_b32 s71, s10, 8
	s_add_i32 s71, s71, s28
	v_or_b32_e32 v176, s71, v186
	v_lshl_or_b32 v174, s11, 8, v188
	s_cmp_lt_i32 s98, 2
	s_mov_b64 s[10:11], -1
	s_cbranch_scc1 .LBB0_151
	s_cmp_lt_i32 s98, 4
	s_cbranch_scc1 .LBB0_84
	s_cmp_lt_i32 s98, 5
	s_cbranch_scc1 .LBB0_65
	s_cmp_lg_u32 s98, 5
	s_cbranch_scc0 .LBB0_62
	v_readlane_b32 s10, v254, 18
	v_ashrrev_i32_e32 v175, 31, v174
	v_readlane_b32 s11, v254, 19
	v_ashrrev_i32_e32 v177, 31, v176
	v_lshlrev_b64 v[130:131], 11, v[176:177]
	v_lshl_add_u64 v[136:137], v[174:175], 1, s[10:11]
	v_or_b32_e32 v190, 16, v176
	v_lshl_add_u64 v[130:131], v[136:137], 0, v[130:131]
	v_ashrrev_i32_e32 v191, 31, v190
	flat_load_dwordx4 v[138:141], v[130:131]
	flat_load_dwordx4 v[142:145], v[130:131] offset:256
	v_lshlrev_b64 v[130:131], 11, v[190:191]
	v_or_b32_e32 v192, 32, v176
	v_lshl_add_u64 v[130:131], v[136:137], 0, v[130:131]
	v_ashrrev_i32_e32 v193, 31, v192
	flat_load_dwordx4 v[146:149], v[130:131]
	flat_load_dwordx4 v[150:153], v[130:131] offset:256
	v_lshlrev_b64 v[130:131], 11, v[192:193]
	v_or_b32_e32 v194, 48, v176
	v_lshl_add_u64 v[130:131], v[136:137], 0, v[130:131]
	v_ashrrev_i32_e32 v195, 31, v194
	flat_load_dwordx4 v[154:157], v[130:131]
	flat_load_dwordx4 v[158:161], v[130:131] offset:256
	v_lshlrev_b64 v[130:131], 11, v[194:195]
	v_lshl_add_u64 v[130:131], v[136:137], 0, v[130:131]
	flat_load_dwordx4 v[178:181], v[130:131]
	s_nop 0
	flat_load_dwordx4 v[130:133], v[130:131] offset:256
	v_readlane_b32 s10, v254, 20
	v_readlane_b32 s11, v254, 21
	s_nop 1
	v_lshl_add_u64 v[134:135], v[174:175], 2, s[10:11]
	v_lshlrev_b64 v[182:183], 12, v[176:177]
	v_lshl_add_u64 v[196:197], v[134:135], 0, v[182:183]
	s_waitcnt vmcnt(0) lgkmcnt(0)
	v_lshlrev_b32_e32 v182, 16, v138
	v_and_b32_e32 v183, 0xffff0000, v138
	v_lshlrev_b32_e32 v138, 16, v139
	v_and_b32_e32 v139, 0xffff0000, v139
	v_pk_add_f32 v[184:185], v[128:129], v[138:139]
	v_lshlrev_b32_e32 v138, 16, v140
	v_and_b32_e32 v139, 0xffff0000, v140
	v_lshlrev_b32_e32 v140, 16, v141
	v_and_b32_e32 v141, 0xffff0000, v141
	v_pk_add_f32 v[182:183], v[126:127], v[182:183]
	v_pk_add_f32 v[138:139], v[122:123], v[138:139]
	v_pk_add_f32 v[140:141], v[124:125], v[140:141]
	global_store_dwordx4 v[196:197], v[182:185], off
	global_store_dwordx4 v[196:197], v[138:141], off offset:16
	s_nop 1
	v_lshlrev_b32_e32 v138, 16, v142
	v_and_b32_e32 v139, 0xffff0000, v142
	v_lshlrev_b32_e32 v140, 16, v143
	v_and_b32_e32 v141, 0xffff0000, v143
	v_pk_add_f32 v[138:139], v[60:61], v[138:139]
	v_pk_add_f32 v[140:141], v[62:63], v[140:141]
	v_lshlrev_b32_e32 v142, 16, v144
	v_and_b32_e32 v143, 0xffff0000, v144
	v_lshlrev_b32_e32 v144, 16, v145
	v_and_b32_e32 v145, 0xffff0000, v145
	v_pk_add_f32 v[142:143], v[56:57], v[142:143]
	v_pk_add_f32 v[144:145], v[58:59], v[144:145]
	global_store_dwordx4 v[196:197], v[138:141], off offset:512
	global_store_dwordx4 v[196:197], v[142:145], off offset:528
	s_nop 0
	v_lshlrev_b64 v[138:139], 12, v[190:191]
	v_lshl_add_u64 v[182:183], v[134:135], 0, v[138:139]
	v_lshlrev_b32_e32 v138, 16, v146
	v_and_b32_e32 v139, 0xffff0000, v146
	v_lshlrev_b32_e32 v140, 16, v147
	v_and_b32_e32 v141, 0xffff0000, v147
	v_pk_add_f32 v[138:139], v[118:119], v[138:139]
	v_pk_add_f32 v[140:141], v[120:121], v[140:141]
	v_lshlrev_b32_e32 v142, 16, v148
	v_and_b32_e32 v143, 0xffff0000, v148
	v_lshlrev_b32_e32 v144, 16, v149
	v_and_b32_e32 v145, 0xffff0000, v149
	v_pk_add_f32 v[142:143], v[114:115], v[142:143]
	v_pk_add_f32 v[144:145], v[116:117], v[144:145]
	global_store_dwordx4 v[182:183], v[138:141], off
	global_store_dwordx4 v[182:183], v[142:145], off offset:16
	s_nop 0
	v_lshlrev_b32_e32 v138, 16, v150
	v_and_b32_e32 v139, 0xffff0000, v150
	v_lshlrev_b32_e32 v140, 16, v151
	v_and_b32_e32 v141, 0xffff0000, v151
	v_pk_add_f32 v[138:139], v[52:53], v[138:139]
	v_pk_add_f32 v[140:141], v[54:55], v[140:141]
	v_lshlrev_b32_e32 v142, 16, v152
	v_and_b32_e32 v143, 0xffff0000, v152
	v_lshlrev_b32_e32 v144, 16, v153
	v_and_b32_e32 v145, 0xffff0000, v153
	v_pk_add_f32 v[142:143], v[48:49], v[142:143]
	v_pk_add_f32 v[144:145], v[50:51], v[144:145]
	global_store_dwordx4 v[182:183], v[138:141], off offset:512
	global_store_dwordx4 v[182:183], v[142:145], off offset:528
	s_nop 0
	v_lshlrev_b64 v[138:139], 12, v[192:193]
	v_lshl_add_u64 v[146:147], v[134:135], 0, v[138:139]
	v_lshlrev_b32_e32 v138, 16, v154
	v_and_b32_e32 v139, 0xffff0000, v154
	v_lshlrev_b32_e32 v140, 16, v155
	v_and_b32_e32 v141, 0xffff0000, v155
	v_pk_add_f32 v[138:139], v[110:111], v[138:139]
	v_pk_add_f32 v[140:141], v[112:113], v[140:141]
	v_lshlrev_b32_e32 v142, 16, v156
	v_and_b32_e32 v143, 0xffff0000, v156
	v_lshlrev_b32_e32 v144, 16, v157
	v_and_b32_e32 v145, 0xffff0000, v157
	v_pk_add_f32 v[142:143], v[106:107], v[142:143]
	v_pk_add_f32 v[144:145], v[108:109], v[144:145]
	global_store_dwordx4 v[146:147], v[138:141], off
	global_store_dwordx4 v[146:147], v[142:145], off offset:16
	s_nop 0
	v_lshlrev_b32_e32 v138, 16, v158
	v_and_b32_e32 v139, 0xffff0000, v158
	v_lshlrev_b32_e32 v140, 16, v159
	v_and_b32_e32 v141, 0xffff0000, v159
	v_pk_add_f32 v[138:139], v[44:45], v[138:139]
	v_pk_add_f32 v[140:141], v[46:47], v[140:141]
	v_lshlrev_b32_e32 v142, 16, v160
	v_and_b32_e32 v143, 0xffff0000, v160
	v_lshlrev_b32_e32 v144, 16, v161
	v_and_b32_e32 v145, 0xffff0000, v161
	v_pk_add_f32 v[142:143], v[40:41], v[142:143]
	v_pk_add_f32 v[144:145], v[42:43], v[144:145]
	global_store_dwordx4 v[146:147], v[138:141], off offset:512
	global_store_dwordx4 v[146:147], v[142:145], off offset:528
; __device__ __forceinline__ float lo16(unsigned v) { return __uint_as_float(v << 16); }
; __device__ __forceinline__ float hi16(unsigned v) { return __uint_as_float(v & 0xffff0000u); }
;   __device__ __forceinline__ void operator()(const f32x4 (&acc)[2][2][4][2], const pg8::Unit& u, int wr, int wc, int fr, int fq) const {
;     ...
; #pragma unroll
;         for (int m = 0; m < 4; ++m) {
;           const int row = row0 + ai * 128 + m * 16;
; #pragma unroll
;           for (int bj = 0; bj < 2; ++bj) {
;             float* d = xo + (size_t)row * DM + col0 + bj * 128;
;             const u32x4 x4 = xv[m][bj];
;             f32x4 o0 = acc[ai][bj][m][0], o1 = acc[ai][bj][m][1];
;             o0[0] += lo16(x4.x); o0[1] += hi16(x4.x); o0[2] += lo16(x4.y); o0[3] += hi16(x4.y); o1[0] += lo16(x4.z); o1[1] += hi16(x4.z); o1[2] += lo16(x4.w); o1[3] += hi16(x4.w);
;             *(f32x4*)d = o0; *(f32x4*)(d + 4) = o1;
;           }
;         }
	s_nop 0
	v_lshlrev_b64 v[138:139], 12, v[194:195]
	v_lshl_add_u64 v[146:147], v[134:135], 0, v[138:139]
	v_lshlrev_b32_e32 v138, 16, v178
	v_and_b32_e32 v139, 0xffff0000, v178
	v_lshlrev_b32_e32 v140, 16, v179
	v_and_b32_e32 v141, 0xffff0000, v179
	v_pk_add_f32 v[138:139], v[102:103], v[138:139]
	v_pk_add_f32 v[140:141], v[104:105], v[140:141]
	v_lshlrev_b32_e32 v142, 16, v180
	v_and_b32_e32 v143, 0xffff0000, v180
	v_lshlrev_b32_e32 v144, 16, v181
	v_and_b32_e32 v145, 0xffff0000, v181
	v_pk_add_f32 v[142:143], v[98:99], v[142:143]
	v_pk_add_f32 v[144:145], v[100:101], v[144:145]
	global_store_dwordx4 v[146:147], v[138:141], off
	global_store_dwordx4 v[146:147], v[142:145], off offset:16
	s_nop 0
	v_lshlrev_b32_e32 v138, 16, v130
	v_and_b32_e32 v139, 0xffff0000, v130
	v_lshlrev_b32_e32 v130, 16, v131
	v_and_b32_e32 v131, 0xffff0000, v131
	v_pk_add_f32 v[138:139], v[36:37], v[138:139]
	v_pk_add_f32 v[140:141], v[38:39], v[130:131]
	v_lshlrev_b32_e32 v130, 16, v132
	v_and_b32_e32 v131, 0xffff0000, v132
	v_lshlrev_b32_e32 v132, 16, v133
	v_and_b32_e32 v133, 0xffff0000, v133
	v_pk_add_f32 v[130:131], v[32:33], v[130:131]
	v_pk_add_f32 v[132:133], v[34:35], v[132:133]
	global_store_dwordx4 v[146:147], v[138:141], off offset:512
	global_store_dwordx4 v[146:147], v[130:133], off offset:528
	v_add_u32_e32 v182, 0x80, v176
	v_ashrrev_i32_e32 v183, 31, v182
	v_lshlrev_b64 v[130:131], 11, v[182:183]
	v_add_u32_e32 v190, 0x90, v176
	v_lshl_add_u64 v[130:131], v[136:137], 0, v[130:131]
	v_ashrrev_i32_e32 v191, 31, v190
	flat_load_dwordx4 v[138:141], v[130:131]
	flat_load_dwordx4 v[142:145], v[130:131] offset:256
	v_lshlrev_b64 v[130:131], 11, v[190:191]
	v_add_u32_e32 v192, 0xa0, v176
	v_lshl_add_u64 v[130:131], v[136:137], 0, v[130:131]
	v_ashrrev_i32_e32 v193, 31, v192
	flat_load_dwordx4 v[146:149], v[130:131]
	flat_load_dwordx4 v[150:153], v[130:131] offset:256
	v_lshlrev_b64 v[130:131], 11, v[192:193]
	v_add_u32_e32 v194, 0xb0, v176
	v_lshl_add_u64 v[130:131], v[136:137], 0, v[130:131]
	v_ashrrev_i32_e32 v195, 31, v194
	flat_load_dwordx4 v[154:157], v[130:131]
	flat_load_dwordx4 v[158:161], v[130:131] offset:256
	v_lshlrev_b64 v[130:131], 11, v[194:195]
	v_lshl_add_u64 v[130:131], v[136:137], 0, v[130:131]
	flat_load_dwordx4 v[178:181], v[130:131]
	s_nop 0
	flat_load_dwordx4 v[130:133], v[130:131] offset:256
	v_lshlrev_b64 v[136:137], 12, v[182:183]
	v_lshl_add_u64 v[196:197], v[134:135], 0, v[136:137]
	s_waitcnt vmcnt(0) lgkmcnt(0)
; __device__ __forceinline__ float lo16(unsigned v) { return __uint_as_float(v << 16); }
; __device__ __forceinline__ float hi16(unsigned v) { return __uint_as_float(v & 0xffff0000u); }
;   __device__ __forceinline__ void operator()(const f32x4 (&acc)[2][2][4][2], const pg8::Unit& u, int wr, int wc, int fr, int fq) const {
;     ...
; #pragma unroll
;         for (int m = 0; m < 4; ++m) {
;           const int row = row0 + ai * 128 + m * 16;
; #pragma unroll
;           for (int bj = 0; bj < 2; ++bj) {
;             float* d = xo + (size_t)row * DM + col0 + bj * 128;
;             const u32x4 x4 = xv[m][bj];
;             f32x4 o0 = acc[ai][bj][m][0], o1 = acc[ai][bj][m][1];
;             o0[0] += lo16(x4.x); o0[1] += hi16(x4.x); o0[2] += lo16(x4.y); o0[3] += hi16(x4.y); o1[0] += lo16(x4.z); o1[1] += hi16(x4.z); o1[2] += lo16(x4.w); o1[3] += hi16(x4.w);
;             *(f32x4*)d = o0; *(f32x4*)(d + 4) = o1;
;           }
;         }
	v_lshlrev_b32_e32 v136, 16, v138
	v_and_b32_e32 v137, 0xffff0000, v138
	v_lshlrev_b32_e32 v138, 16, v139
	v_and_b32_e32 v139, 0xffff0000, v139
	v_pk_add_f32 v[136:137], v[94:95], v[136:137]
	v_pk_add_f32 v[138:139], v[96:97], v[138:139]
	v_lshlrev_b32_e32 v182, 16, v140
	v_and_b32_e32 v183, 0xffff0000, v140
	v_lshlrev_b32_e32 v140, 16, v141
	v_and_b32_e32 v141, 0xffff0000, v141
	v_pk_add_f32 v[182:183], v[90:91], v[182:183]
	v_pk_add_f32 v[184:185], v[92:93], v[140:141]
	global_store_dwordx4 v[196:197], v[136:139], off
	global_store_dwordx4 v[196:197], v[182:185], off offset:16
	v_lshlrev_b32_e32 v140, 16, v144
	v_lshlrev_b32_e32 v136, 16, v142
	v_and_b32_e32 v137, 0xffff0000, v142
	v_lshlrev_b32_e32 v138, 16, v143
	v_and_b32_e32 v139, 0xffff0000, v143
	v_pk_add_f32 v[136:137], v[28:29], v[136:137]
	v_pk_add_f32 v[138:139], v[30:31], v[138:139]
	v_and_b32_e32 v141, 0xffff0000, v144
	v_lshlrev_b32_e32 v142, 16, v145
	v_and_b32_e32 v143, 0xffff0000, v145
	v_pk_add_f32 v[140:141], v[24:25], v[140:141]
	v_pk_add_f32 v[142:143], v[26:27], v[142:143]
	global_store_dwordx4 v[196:197], v[136:139], off offset:512
	global_store_dwordx4 v[196:197], v[140:143], off offset:528
	s_nop 0
	v_lshlrev_b64 v[136:137], 12, v[190:191]
	v_lshl_add_u64 v[144:145], v[134:135], 0, v[136:137]
	v_lshlrev_b32_e32 v136, 16, v146
	v_and_b32_e32 v137, 0xffff0000, v146
	v_lshlrev_b32_e32 v138, 16, v147
	v_and_b32_e32 v139, 0xffff0000, v147
	v_pk_add_f32 v[136:137], v[86:87], v[136:137]
	v_pk_add_f32 v[138:139], v[88:89], v[138:139]
	v_lshlrev_b32_e32 v140, 16, v148
	v_and_b32_e32 v141, 0xffff0000, v148
	v_lshlrev_b32_e32 v142, 16, v149
	v_and_b32_e32 v143, 0xffff0000, v149
	v_pk_add_f32 v[140:141], v[82:83], v[140:141]
	v_pk_add_f32 v[142:143], v[84:85], v[142:143]
	global_store_dwordx4 v[144:145], v[136:139], off
	global_store_dwordx4 v[144:145], v[140:143], off offset:16
	s_nop 0
	v_lshlrev_b32_e32 v136, 16, v150
	v_and_b32_e32 v137, 0xffff0000, v150
	v_lshlrev_b32_e32 v138, 16, v151
	v_and_b32_e32 v139, 0xffff0000, v151
	v_pk_add_f32 v[136:137], v[20:21], v[136:137]
	v_pk_add_f32 v[138:139], v[22:23], v[138:139]
	v_lshlrev_b32_e32 v140, 16, v152
	v_and_b32_e32 v141, 0xffff0000, v152
	v_lshlrev_b32_e32 v142, 16, v153
	v_and_b32_e32 v143, 0xffff0000, v153
	v_pk_add_f32 v[140:141], v[16:17], v[140:141]
	v_pk_add_f32 v[142:143], v[18:19], v[142:143]
	global_store_dwordx4 v[144:145], v[136:139], off offset:512
	global_store_dwordx4 v[144:145], v[140:143], off offset:528
	s_nop 0
	v_lshlrev_b64 v[136:137], 12, v[192:193]
	v_lshl_add_u64 v[144:145], v[134:135], 0, v[136:137]
	v_lshlrev_b32_e32 v136, 16, v154
	v_and_b32_e32 v137, 0xffff0000, v154
	v_lshlrev_b32_e32 v138, 16, v155
	v_and_b32_e32 v139, 0xffff0000, v155
	v_pk_add_f32 v[136:137], v[76:77], v[136:137]
	v_pk_add_f32 v[138:139], v[78:79], v[138:139]
	v_lshlrev_b32_e32 v140, 16, v156
	v_and_b32_e32 v141, 0xffff0000, v156
	v_lshlrev_b32_e32 v142, 16, v157
	v_and_b32_e32 v143, 0xffff0000, v157
	v_pk_add_f32 v[140:141], v[72:73], v[140:141]
	v_pk_add_f32 v[142:143], v[74:75], v[142:143]
	global_store_dwordx4 v[144:145], v[136:139], off
	global_store_dwordx4 v[144:145], v[140:143], off offset:16
	s_nop 0
	v_lshlrev_b32_e32 v136, 16, v158
	v_and_b32_e32 v137, 0xffff0000, v158
	v_lshlrev_b32_e32 v138, 16, v159
	v_and_b32_e32 v139, 0xffff0000, v159
	v_pk_add_f32 v[136:137], v[12:13], v[136:137]
	v_pk_add_f32 v[138:139], v[14:15], v[138:139]
	v_lshlrev_b32_e32 v140, 16, v160
	v_and_b32_e32 v141, 0xffff0000, v160
	v_lshlrev_b32_e32 v142, 16, v161
	v_and_b32_e32 v143, 0xffff0000, v161
	v_pk_add_f32 v[140:141], v[8:9], v[140:141]
	v_pk_add_f32 v[142:143], v[10:11], v[142:143]
	global_store_dwordx4 v[144:145], v[136:139], off offset:512
	global_store_dwordx4 v[144:145], v[140:143], off offset:528
	s_nop 0
	v_lshlrev_b64 v[136:137], 12, v[194:195]
	v_lshl_add_u64 v[142:143], v[134:135], 0, v[136:137]
	v_lshlrev_b32_e32 v134, 16, v178
	v_and_b32_e32 v135, 0xffff0000, v178
	v_lshlrev_b32_e32 v136, 16, v179
	v_and_b32_e32 v137, 0xffff0000, v179
	v_pk_add_f32 v[134:135], v[68:69], v[134:135]
	v_pk_add_f32 v[136:137], v[70:71], v[136:137]
	v_lshlrev_b32_e32 v138, 16, v180
	v_and_b32_e32 v139, 0xffff0000, v180
	v_lshlrev_b32_e32 v140, 16, v181
	v_and_b32_e32 v141, 0xffff0000, v181
	v_pk_add_f32 v[138:139], v[64:65], v[138:139]
	v_pk_add_f32 v[140:141], v[66:67], v[140:141]
	global_store_dwordx4 v[142:143], v[134:137], off
	global_store_dwordx4 v[142:143], v[138:141], off offset:16
	s_nop 0
	v_lshlrev_b32_e32 v134, 16, v130
	v_and_b32_e32 v135, 0xffff0000, v130
	v_lshlrev_b32_e32 v130, 16, v131
	v_and_b32_e32 v131, 0xffff0000, v131
	v_pk_add_f32 v[134:135], v[4:5], v[134:135]
	v_pk_add_f32 v[136:137], v[6:7], v[130:131]
	v_lshlrev_b32_e32 v130, 16, v132
	v_and_b32_e32 v131, 0xffff0000, v132
	v_lshlrev_b32_e32 v132, 16, v133
	v_and_b32_e32 v133, 0xffff0000, v133
	v_pk_add_f32 v[130:131], v[0:1], v[130:131]
	v_pk_add_f32 v[132:133], v[2:3], v[132:133]
	global_store_dwordx4 v[142:143], v[134:137], off offset:512
	global_store_dwordx4 v[142:143], v[130:133], off offset:528
	s_mov_b64 s[10:11], 0
